# MLA GEMM rebalancing: D-in round 0, barrier, then remaining D-in rounds (copy of the phase starting at blockIdx+gridDim) followed by D-up with 4 tiles on WGs 0-63 and 8 on WGs 64-255 (removes the 192-
# speedup vs baseline: 1.0191x; 1.0048x over previous
; #define PG8_STAGE(bufoff, gbase, voff) do { _Pragma("unroll") for (int _i = 0; _i < 2; ++_i) \
;         __builtin_amdgcn_global_load_lds((const unsigned*)((const char*)(gbase) + (voff)[_i]), (LAS unsigned*)(lds + (bufoff) + ldsw + _i * 8192), 16, 0, 0); } while (0)
; #define PG8_WAIT_V(n) asm volatile("s_waitcnt vmcnt(" #n ")" ::: "memory")
; #define PG8_BAR __builtin_amdgcn_s_barrier()
;     DI bool next(int i, Unit& u) const {
;         const long L = (long)i * G + c; if (L >= nwg) return false;
;         int wgid = (int)L; { const int q = nwg / NXCD, r = nwg % NXCD, xcd = wgid % NXCD, off = wgid / NXCD; wgid = (xcd < r ? xcd * (q + 1) : r * (q + 1) + (xcd - r) * q) + off; }
; template <class Epi, class SchedT>
; DI void gemm_phase(LAS unsigned char* lds, const bf16_t* Ap, const bf16_t* Btp, const int K, const int lda, const SchedT& S, const Epi& E) {
;     ...
;     PG8_STAGE(PG8_SB(0, 0), cB, voffB); PG8_STAGE(PG8_SA(0, 0), cA, voffA); PG8_STAGE(PG8_SB(0, 1), cB + hstepB, voffB); PG8_STAGE(PG8_SA(0, 1), cA + hstepA, voffA);
;     if (wr == 1) PG8_BAR;
;     PG8_WAIT_V(4); PG8_BAR;
;     PG8_STAGE(PG8_SB(1, 0), cB + kstep, voffB); PG8_STAGE(PG8_SA(1, 0), cA + kstep, voffA); PG8_STAGE(PG8_SB(1, 1), cB + hstepB + kstep, voffB);
;     PG8_WAIT_V(6); PG8_BAR;
;     for (;;) {
;         const bool has_next = S.next(ui + 1, nxt);
.LBB0_1174:
	s_add_u32 s28, s16, 0x7f00000
	s_addc_u32 s29, s17, 0
	s_add_u32 s66, s16, 0x1ff40000
	s_mov_b64 s[30:31], 0x80
	s_addc_u32 s67, s17, 0
	s_add_i32 m0, s59, 0x18000
	v_lshl_add_u64 v[10:11], v[10:11], 0, s[30:31]
	s_waitcnt vmcnt(4)
	s_barrier
	global_load_lds_dwordx4 v[10:11], off
	v_lshl_add_u64 v[8:9], v[8:9], 0, s[30:31]
	s_add_i32 m0, s59, 0x1a000
	s_add_i32 s68, s59, 0x8000
	global_load_lds_dwordx4 v[8:9], off
	v_lshl_add_u64 v[6:7], v[6:7], 0, s[30:31]
	s_mov_b32 m0, s68
	s_add_i32 s69, s59, 0xa000
	global_load_lds_dwordx4 v[6:7], off
	v_lshl_add_u64 v[4:5], v[4:5], 0, s[30:31]
	s_mov_b32 m0, s69
	v_lshl_add_u64 v[2:3], v[2:3], 0, s[30:31]
	global_load_lds_dwordx4 v[4:5], off
	s_add_i32 m0, s59, 0x1c000
	v_lshl_add_u64 v[0:1], v[0:1], 0, s[30:31]
	global_load_lds_dwordx4 v[2:3], off
	s_add_i32 m0, s59, 0x1e000
	s_lshr_b32 s6, s9, 26
	global_load_lds_dwordx4 v[0:1], off
	v_bfe_u32 v0, v12, 4, 2
	s_add_i32 s6, s8, s6
	v_or_b32_e32 v160, s35, v19
	s_ashr_i32 s70, s6, 6
	v_lshlrev_b32_e32 v1, 6, v160
	v_lshlrev_b32_e32 v2, 4, v0
	s_movk_i32 s6, 0x3c0
	v_lshlrev_b32_e32 v3, 2, v160
	v_and_or_b32 v1, v1, s6, v2
	s_lshl_b32 s6, s11, 13
	v_and_b32_e32 v3, 32, v3
	v_bitop3_b32 v1, v1, s6, v3 bitop3:0xde
	s_lshl_b32 s6, s34, 5
	s_and_b32 s71, s6, 0x60
	v_lshlrev_b32_e32 v3, 2, v19
	v_lshl_or_b32 v2, v19, 6, v2
	s_lshl_b32 s6, s71, 7
	v_and_b32_e32 v3, 32, v3
	v_lshlrev_b32_e32 v161, 3, v0
	v_bitop3_b32 v162, v2, s6, v3 bitop3:0xde
	v_cmp_eq_u32_e64 s[6:7], 0, v0
	v_lshlrev_b32_e32 v0, 15, v16
	v_and_b32_e32 v0, 0xffff0000, v0
	v_lshl_add_u32 v0, v17, 12, v0
	v_and_b32_e32 v2, 1, v16
	v_lshl_or_b32 v0, v2, 6, v0
	v_lshl_add_u32 v138, v18, 1, v0
	v_lshlrev_b32_e32 v0, 15, v13
	v_and_b32_e32 v0, 0xffff0000, v0
	s_waitcnt vmcnt(6)
	s_cmp_gt_i32 s8, 63
	v_lshl_add_u32 v0, v14, 12, v0
	v_and_b32_e32 v2, 1, v13
	s_cselect_b64 s[34:35], -1, 0
	v_lshl_or_b32 v0, v2, 6, v0
	s_add_i32 s77, 0, 0x10000
	s_add_i32 s78, 0, 0x14000
	s_add_i32 s72, s70, -2
	s_ashr_i32 s73, s18, 31
	s_mov_b32 s74, s18
	s_ashr_i32 s75, s2, 31
	s_lshl_b64 s[36:37], s[8:9], 9
	v_mov_b32_e32 v139, v137
	v_lshl_add_u32 v140, v15, 1, v0
	v_mov_b32_e32 v141, v137
	v_mov_b64_e32 v[142:143], 0x100
	v_mov_b64_e32 v[144:145], 0xff
	s_movk_i32 s76, 0x69
	v_add_u32_e32 v163, s77, v162
	v_add_u32_e32 v164, 0, v1
	v_add_u32_e32 v165, s78, v162
	v_mov_b32_e32 v166, 0x358637bd
	s_mov_b32 s79, 0x800000
	s_movk_i32 s80, 0x880
	s_movk_i32 s81, 0x43f
	s_movk_i32 s82, 0xc40
	v_mbcnt_hi_u32_b32 v167, -1, v178
	s_barrier
	s_branch .LBB0_1176

; #define PG8_WAIT_V(n) asm volatile("s_waitcnt vmcnt(" #n ")" ::: "memory")
; #define PG8_BAR __builtin_amdgcn_s_barrier()
;     DI bool next(int i, Unit& u) const {
;         const long L = (long)i * G + c; if (L >= nwg) return false;
;         int wgid = (int)L; { const int q = nwg / NXCD, r = nwg % NXCD, xcd = wgid % NXCD, off = wgid / NXCD; wgid = (xcd < r ? xcd * (q + 1) : r * (q + 1) + (xcd - r) * q) + off; }
;         const int nig = WGM * nN, gid = wgid / nig, fm = gid * WGM, gsz = (nM - fm) < WGM ? (nM - fm) : WGM;
;         u.pm = fm + ((wgid % nig) % gsz); u.pn = (wgid % nig) / gsz;
;         u.aoff = (size_t)u.pm * 256 * lda * 2; u.boff = (size_t)u.pn * 256 * K * 2;
; template <class Epi, class SchedT>
; DI void gemm_phase(LAS unsigned char* lds, const bf16_t* Ap, const bf16_t* Btp, const int K, const int lda, const SchedT& S, const Epi& E) {
;     ...
;     PG8_WAIT_V(0);
;     if (wr == 0) PG8_BAR;
;     PG8_BAR;
.LBB0_1358:
	s_or_b64 exec, exec, s[6:7]
	s_waitcnt lgkmcnt(0)
	s_barrier
	s_add_i32 s93, s2, s18
	s_load_dwordx2 s[16:17], s[0:1], 0xf0
	s_movk_i32 s8, 0x800
	s_ashr_i32 s9, s8, 31
	v_mov_b32_e32 v12, v181
	s_cmpk_lt_i32 s93, 0x340
	s_cselect_b64 s[14:15], -1, 0
	s_cmpk_gt_i32 s93, 0x33f
	v_readfirstlane_b32 s3, v12
	s_cbranch_scc1 .Ldi_1171
	s_ashr_i32 s6, s93, 31
	s_lshr_b32 s6, s6, 29
	s_add_i32 s6, s93, s6
	s_ashr_i32 s7, s6, 3
	s_and_b32 s6, s6, -8
	s_sub_i32 s6, s93, s6
	s_cmp_lt_i32 s6, 0
	s_movk_i32 s10, 0x69
	s_cselect_b32 s10, s10, 0x68
	s_mul_i32 s6, s10, s6
	s_add_i32 s6, s6, s7
	s_mul_hi_i32 s7, s6, 0x4ec4ec4f
	s_lshr_b32 s10, s7, 31
	s_ashr_i32 s7, s7, 5
	s_add_i32 s7, s7, s10
	s_lshl_b32 s10, s7, 3
	s_mulk_i32 s7, 0x68
	s_sub_i32 s6, s6, s7
	s_bfe_i32 s7, s6, 0x80000
	s_bfe_u32 s7, s7, 0x3000c
	s_add_i32 s7, s6, s7
	s_bfe_i32 s11, s7, 0x80000
	s_and_b32 s7, s7, 0xf8
	s_sub_i32 s6, s6, s7
	s_sext_i32_i16 s11, s11
	s_sext_i32_i8 s6, s6
	s_add_i32 s10, s10, s6
	s_ashr_i32 s52, s11, 3
	s_ashr_i32 s11, s10, 31
	s_mul_hi_i32 s13, s52, s8
	s_mul_i32 s12, s52, s8
	s_lshl_b64 s[6:7], s[10:11], 20
	s_lshl_b64 s[12:13], s[12:13], 9
	s_andn2_b64 vcc, exec, s[14:15]
	s_cbranch_vccz .Ldi_1172
	s_branch .Ldi_1306

; #define PG8_STAGE(bufoff, gbase, voff) do { _Pragma("unroll") for (int _i = 0; _i < 2; ++_i) \
;         __builtin_amdgcn_global_load_lds((const unsigned*)((const char*)(gbase) + (voff)[_i]), (LAS unsigned*)(lds + (bufoff) + ldsw + _i * 8192), 16, 0, 0); } while (0)
; #define PG8_WAIT_V(n) asm volatile("s_waitcnt vmcnt(" #n ")" ::: "memory")
; #define PG8_BAR __builtin_amdgcn_s_barrier()
;     DI bool next(int i, Unit& u) const {
;         const long L = (long)i * G + c; if (L >= nwg) return false;
;         int wgid = (int)L; { const int q = nwg / NXCD, r = nwg % NXCD, xcd = wgid % NXCD, off = wgid / NXCD; wgid = (xcd < r ? xcd * (q + 1) : r * (q + 1) + (xcd - r) * q) + off; }
; template <class Epi, class SchedT>
; DI void gemm_phase(LAS unsigned char* lds, const bf16_t* Ap, const bf16_t* Btp, const int K, const int lda, const SchedT& S, const Epi& E) {
;     ...
;     PG8_STAGE(PG8_SB(0, 0), cB, voffB); PG8_STAGE(PG8_SA(0, 0), cA, voffA); PG8_STAGE(PG8_SB(0, 1), cB + hstepB, voffB); PG8_STAGE(PG8_SA(0, 1), cA + hstepA, voffA);
;     if (wr == 1) PG8_BAR;
;     PG8_WAIT_V(4); PG8_BAR;
;     PG8_STAGE(PG8_SB(1, 0), cB + kstep, voffB); PG8_STAGE(PG8_SA(1, 0), cA + kstep, voffA); PG8_STAGE(PG8_SB(1, 1), cB + hstepB + kstep, voffB);
;     PG8_WAIT_V(6); PG8_BAR;
;     for (;;) {
;         const bool has_next = S.next(ui + 1, nxt);
.Ldi_1174:
	s_add_u32 s28, s16, 0x7f00000
	s_addc_u32 s29, s17, 0
	s_add_u32 s66, s16, 0x1ff40000
	s_mov_b64 s[30:31], 0x80
	s_addc_u32 s67, s17, 0
	s_add_i32 m0, s59, 0x18000
	v_lshl_add_u64 v[10:11], v[10:11], 0, s[30:31]
	s_waitcnt vmcnt(4)
	s_barrier
	global_load_lds_dwordx4 v[10:11], off
	v_lshl_add_u64 v[8:9], v[8:9], 0, s[30:31]
	s_add_i32 m0, s59, 0x1a000
	s_add_i32 s68, s59, 0x8000
	global_load_lds_dwordx4 v[8:9], off
	v_lshl_add_u64 v[6:7], v[6:7], 0, s[30:31]
	s_mov_b32 m0, s68
	s_add_i32 s69, s59, 0xa000
	global_load_lds_dwordx4 v[6:7], off
	v_lshl_add_u64 v[4:5], v[4:5], 0, s[30:31]
	s_mov_b32 m0, s69
	v_lshl_add_u64 v[2:3], v[2:3], 0, s[30:31]
	global_load_lds_dwordx4 v[4:5], off
	s_add_i32 m0, s59, 0x1c000
	v_lshl_add_u64 v[0:1], v[0:1], 0, s[30:31]
	global_load_lds_dwordx4 v[2:3], off
	s_add_i32 m0, s59, 0x1e000
	s_lshr_b32 s6, s9, 26
	global_load_lds_dwordx4 v[0:1], off
	v_bfe_u32 v0, v12, 4, 2
	s_add_i32 s6, s8, s6
	v_or_b32_e32 v160, s35, v19
	s_ashr_i32 s70, s6, 6
	v_lshlrev_b32_e32 v1, 6, v160
	v_lshlrev_b32_e32 v2, 4, v0
	s_movk_i32 s6, 0x3c0
	v_lshlrev_b32_e32 v3, 2, v160
	v_and_or_b32 v1, v1, s6, v2
	s_lshl_b32 s6, s11, 13
	v_and_b32_e32 v3, 32, v3
	v_bitop3_b32 v1, v1, s6, v3 bitop3:0xde
	s_lshl_b32 s6, s34, 5
	s_and_b32 s71, s6, 0x60
	v_lshlrev_b32_e32 v3, 2, v19
	v_lshl_or_b32 v2, v19, 6, v2
	s_lshl_b32 s6, s71, 7
	v_and_b32_e32 v3, 32, v3
	v_lshlrev_b32_e32 v161, 3, v0
	v_bitop3_b32 v162, v2, s6, v3 bitop3:0xde
	v_cmp_eq_u32_e64 s[6:7], 0, v0
	v_lshlrev_b32_e32 v0, 15, v16
	v_and_b32_e32 v0, 0xffff0000, v0
	v_lshl_add_u32 v0, v17, 12, v0
	v_and_b32_e32 v2, 1, v16
	v_lshl_or_b32 v0, v2, 6, v0
	v_lshl_add_u32 v138, v18, 1, v0
	v_lshlrev_b32_e32 v0, 15, v13
	v_and_b32_e32 v0, 0xffff0000, v0
	s_waitcnt vmcnt(6)
	s_cmp_gt_i32 s8, 63
	v_lshl_add_u32 v0, v14, 12, v0
	v_and_b32_e32 v2, 1, v13
	s_cselect_b64 s[34:35], -1, 0
	v_lshl_or_b32 v0, v2, 6, v0
	s_add_i32 s77, 0, 0x10000
	s_add_i32 s78, 0, 0x14000
	s_add_i32 s72, s70, -2
	s_ashr_i32 s73, s18, 31
	s_mov_b32 s74, s18
	s_ashr_i32 s75, s93, 31
	s_lshl_b64 s[36:37], s[8:9], 9
	v_mov_b32_e32 v139, v137
	v_lshl_add_u32 v140, v15, 1, v0
	v_mov_b32_e32 v141, v137
	v_mov_b64_e32 v[142:143], 0x340
	v_mov_b64_e32 v[144:145], 0x33f
	s_movk_i32 s76, 0x69
	v_add_u32_e32 v163, s77, v162
	v_add_u32_e32 v164, 0, v1
	v_add_u32_e32 v165, s78, v162
	v_mov_b32_e32 v166, 0x358637bd
	s_mov_b32 s79, 0x800000
	s_movk_i32 s80, 0x880
	s_movk_i32 s81, 0x43f
	s_movk_i32 s82, 0xc40
	v_mbcnt_hi_u32_b32 v167, -1, v178
	s_barrier
	s_branch .Ldi_1176

;     DI bool next(int i, Unit& u) const {
;         const long L = (long)i * G + c; if (L >= nwg) return false;
;         int wgid = (int)L; { const int q = nwg / NXCD, r = nwg % NXCD, xcd = wgid % NXCD, off = wgid / NXCD; wgid = (xcd < r ? xcd * (q + 1) : r * (q + 1) + (xcd - r) * q) + off; }
;         const int nig = WGM * nN, gid = wgid / nig, fm = gid * WGM, gsz = (nM - fm) < WGM ? (nM - fm) : WGM;
;         u.pm = fm + ((wgid % nig) % gsz); u.pn = (wgid % nig) / gsz;
;         u.aoff = (size_t)u.pm * 256 * lda * 2; u.boff = (size_t)u.pn * 256 * K * 2;
.Ldi_1176:
	s_add_i32 s65, s65, 1
	s_mul_i32 s8, s65, s73
	s_mul_hi_u32 s9, s65, s74
	s_add_i32 s9, s9, s8
	s_mul_i32 s8, s65, s74
	s_add_u32 s44, s8, s93
	s_addc_u32 s45, s9, s75
	v_cmp_gt_i64_e32 vcc, s[44:45], v[144:145]
	v_cmp_lt_i64_e64 s[8:9], s[44:45], v[142:143]
	s_cbranch_vccnz .Ldi_1178
	s_ashr_i32 s11, s44, 31
	s_lshr_b32 s11, s11, 29
	s_add_i32 s11, s44, s11
	s_ashr_i32 s38, s11, 3
	s_and_b32 s11, s11, -8
	s_sub_i32 s11, s44, s11
	s_cmp_lt_i32 s11, 0
	s_cselect_b32 s39, s76, 0x68
	s_mul_i32 s11, s39, s11
	s_add_i32 s11, s11, s38
	s_mul_hi_i32 s38, s11, 0x4ec4ec4f
	s_lshr_b32 s39, s38, 31
	s_ashr_i32 s38, s38, 5
	s_add_i32 s38, s38, s39
	s_lshl_b32 s39, s38, 3
	s_sub_i32 s40, 64, s39
	s_min_i32 s40, s40, 8
	s_abs_i32 s41, s40
	v_cvt_f32_u32_e32 v0, s41
	s_sub_i32 s43, 0, s41
	s_mulk_i32 s38, 0x68
	s_sub_i32 s11, s11, s38
	v_rcp_iflag_f32_e32 v0, v0
	s_abs_i32 s38, s11
	s_xor_b32 s42, s11, s40
	s_ashr_i32 s42, s42, 31
	v_mul_f32_e32 v0, 0x4f7ffffe, v0
	v_cvt_u32_f32_e32 v0, v0
	s_nop 0
	v_readfirstlane_b32 s44, v0
	s_mul_i32 s43, s43, s44
	s_mul_hi_u32 s43, s44, s43
	s_add_i32 s44, s44, s43
	s_mul_hi_u32 s43, s38, s44
	s_mul_i32 s44, s43, s41
	s_sub_i32 s38, s38, s44
	s_add_i32 s45, s43, 1
	s_sub_i32 s44, s38, s41
	s_cmp_ge_u32 s38, s41
	s_cselect_b32 s43, s45, s43
	s_cselect_b32 s38, s44, s38
	s_add_i32 s44, s43, 1
	s_cmp_ge_u32 s38, s41
	s_cselect_b32 s38, s44, s43
	s_xor_b32 s38, s38, s42
	s_sub_i32 s83, s38, s42
	s_mul_i32 s38, s83, s40
	s_sub_i32 s11, s11, s38
	s_add_i32 s38, s11, s39
	s_ashr_i32 s39, s38, 31
	s_ashr_i32 s11, s83, 31
	s_lshl_b64 s[40:41], s[38:39], 20
	s_mul_i32 s11, s36, s11
	s_mul_hi_u32 s39, s36, s83
	s_add_i32 s11, s39, s11
	s_mul_i32 s39, s37, s83
	s_add_i32 s43, s11, s39
	s_mul_i32 s42, s36, s83

; #define PG8_STAGE(bufoff, gbase, voff) do { _Pragma("unroll") for (int _i = 0; _i < 2; ++_i) \
;         __builtin_amdgcn_global_load_lds((const unsigned*)((const char*)(gbase) + (voff)[_i]), (LAS unsigned*)(lds + (bufoff) + ldsw + _i * 8192), 16, 0, 0); } while (0)
; #define PG8_WAIT_V(n) asm volatile("s_waitcnt vmcnt(" #n ")" ::: "memory")
; #define PG8_BAR __builtin_amdgcn_s_barrier()
;     DI bool next(int i, Unit& u) const {
;         const long L = (long)i * G + c; if (L >= nwg) return false;
;         int wgid = (int)L; { const int q = nwg / NXCD, r = nwg % NXCD, xcd = wgid % NXCD, off = wgid / NXCD; wgid = (xcd < r ? xcd * (q + 1) : r * (q + 1) + (xcd - r) * q) + off; }
;         const int nig = WGM * nN, gid = wgid / nig, fm = gid * WGM, gsz = (nM - fm) < WGM ? (nM - fm) : WGM;
;         u.pm = fm + ((wgid % nig) % gsz); u.pn = (wgid % nig) / gsz;
;         u.aoff = (size_t)u.pm * 256 * lda * 2; u.boff = (size_t)u.pn * 256 * K * 2;
;         if (MODE == 1 && u.pn >= 12) u.aoff += 1024;
;         if (MODE == 2) u.aoff += (size_t)(u.pn >> 1) * 512;
; template <class Epi, class SchedT>
; DI void gemm_phase(LAS unsigned char* lds, const bf16_t* Ap, const bf16_t* Btp, const int K, const int lda, const SchedT& S, const Epi& E) {
;     ...
;     PG8_STAGE(PG8_SB(0, 0), cB, voffB); PG8_STAGE(PG8_SA(0, 0), cA, voffA); PG8_STAGE(PG8_SB(0, 1), cB + hstepB, voffB); PG8_STAGE(PG8_SA(0, 1), cA + hstepA, voffA);
;     if (wr == 1) PG8_BAR;
;     PG8_WAIT_V(4); PG8_BAR;
;     PG8_STAGE(PG8_SB(1, 0), cB + kstep, voffB); PG8_STAGE(PG8_SA(1, 0), cA + kstep, voffA); PG8_STAGE(PG8_SB(1, 1), cB + hstepB + kstep, voffB);
;     PG8_WAIT_V(6); PG8_BAR;
.Ldi_1306:
	s_waitcnt lgkmcnt(0)
	s_barrier
	s_lshl_b32 s94, s2, 2
	s_addk_i32 s94, 0x600
	s_sub_i32 s95, s2, 64
	s_lshl_b32 s95, s95, 3
	s_cmp_lt_u32 s2, 64
	s_cselect_b32 s94, s94, s95
	s_cselect_b32 s95, 4, 8
	s_add_i32 s95, s94, s95
	s_add_i32 s92, s95, -1
	s_load_dwordx2 s[8:9], s[0:1], 0xf0
	s_movk_i32 s6, 0x200
	v_mov_b32_e32 v14, v181
	s_cmpk_gt_i32 s94, 0x6ff
	v_readfirstlane_b32 s3, v14
	s_cbranch_scc1 .LBB0_1373
	v_lshlrev_b32_e32 v0, 4, v14
	v_add_u32_e32 v1, 0x2000, v0
	v_ashrrev_i32_e32 v2, 31, v1
	v_lshrrev_b32_e32 v2, 22, v2
	v_add_u32_e32 v2, v1, v2
	v_ashrrev_i32_e32 v12, 10, v2
	v_mul_i32_i24_e32 v2, 0x400, v12
	v_sub_u32_e32 v1, v1, v2
	v_lshrrev_b32_e32 v2, 4, v1
	v_bitop3_b32 v1, v2, v1, 32 bitop3:0x6c
	v_ashrrev_i32_e32 v2, 31, v1
	v_lshrrev_b32_e32 v2, 26, v2
	v_add_u32_e32 v2, v1, v2
	v_lshlrev_b32_e32 v3, 3, v12
	v_ashrrev_i32_e32 v15, 6, v2
	v_and_b32_e32 v3, -16, v3
	v_add_u32_e32 v3, v15, v3
	v_and_b32_e32 v4, 3, v15
	s_mov_b32 s12, 0x7fffffe0
	v_lshrrev_b32_e32 v5, 2, v3
	v_lshlrev_b32_e32 v6, 1, v3
	v_and_b32_e32 v2, 0xc0, v2
	v_and_or_b32 v4, v3, s12, v4
	v_and_b32_e32 v5, 4, v5
	v_and_b32_e32 v6, 24, v6
	v_sub_u32_e32 v1, v1, v2
	v_mov_b32_e32 v2, 1
	v_or3_b32 v4, v4, v5, v6
	v_lshlrev_b32_e32 v5, 5, v12
	v_ashrrev_i16_sdwa v1, v2, sext(v1) dst_sel:DWORD dst_unused:UNUSED_PAD src0_sel:DWORD src1_sel:BYTE_0
	v_and_b32_e32 v16, 32, v5
	v_bfe_i32 v17, v1, 0, 16
	s_movk_i32 s27, 0x440
	v_mul_lo_u32 v4, v4, s6
	v_add_u32_e32 v1, v16, v17
	v_mul_lo_u32 v3, v3, s27
	v_add_lshl_u32 v128, v4, v1, 1
	v_add_lshl_u32 v130, v1, v3, 1
	v_bfe_i32 v1, v14, 27, 1
	v_lshrrev_b32_e32 v1, 22, v1
	v_add_u32_e32 v1, v0, v1
	v_and_b32_e32 v1, 0xfffffc00, v1
	v_sub_u32_e32 v0, v0, v1
	v_lshrrev_b32_e32 v1, 4, v0
	v_bitop3_b32 v1, v1, v0, 32 bitop3:0x6c
	v_ashrrev_i32_e32 v0, 31, v0
	v_lshrrev_b32_e32 v0, 26, v0
	v_add_u32_e32 v0, v1, v0
	v_ashrrev_i32_e32 v18, 6, v0
	v_ashrrev_i32_e32 v0, 31, v14
	v_lshrrev_b32_e32 v0, 26, v0
	v_add_u32_e32 v0, v14, v0
	s_waitcnt lgkmcnt(0)
	s_add_u32 s44, s8, 0x1ff40000
	v_ashrrev_i32_e32 v19, 6, v0
	s_addc_u32 s45, s9, 0
	v_lshlrev_b32_e32 v0, 3, v19
	s_add_u32 s46, s8, 0x7000000
	v_and_b32_e32 v0, -16, v0
	s_addc_u32 s47, s9, 0
	v_add_u32_e32 v0, v18, v0
	v_and_b32_e32 v3, 3, v18
	s_ashr_i32 s49, s94, 31
	v_and_or_b32 v3, v0, s12, v3
	s_lshr_b32 s12, s49, 29
	s_add_i32 s12, s94, s12
	s_ashr_i32 s25, s3, 6
	s_ashr_i32 s26, s3, 8
	s_ashr_i32 s7, s6, 31
	s_ashr_i32 s13, s12, 3
	s_and_b32 s12, s12, -8
	s_lshl_b64 s[10:11], s[6:7], 8
	s_lshl_b32 s48, s25, 10
	s_lshl_b32 s28, s26, 6
	s_sub_i32 s12, s94, s12
	s_cmp_lt_i32 s12, 0
	s_movk_i32 s50, 0xe1
	s_cselect_b32 s14, s50, 0xe0
	s_mul_i32 s12, s14, s12
	s_add_i32 s12, s12, s13
	s_mul_hi_i32 s13, s12, 0x92492493
	s_add_i32 s13, s13, s12
	s_lshr_b32 s14, s13, 31
	s_ashr_i32 s13, s13, 7
	s_add_i32 s13, s13, s14
	s_lshl_b32 s14, s13, 3
	s_mulk_i32 s13, 0xe0
	s_sub_i32 s16, s12, s13
	s_sext_i32_i16 s12, s16
	s_bfe_u32 s12, s12, 0x3001c
	s_add_i32 s12, s16, s12
	s_sext_i32_i16 s17, s12
	s_and_b32 s12, s12, 0xfff8
	s_sub_i32 s12, s16, s12
	s_lshr_b32 s24, s17, 3
	s_sext_i32_i16 s12, s12
	s_add_i32 s70, s14, s12
	s_bfe_i64 s[14:15], s[24:25], 0x100000
	s_lshl_b64 s[12:13], s[6:7], 9
	s_ashr_i32 s17, s17, 3
	s_mul_hi_u32 s14, s12, s17
	s_mul_i32 s15, s12, s15
	v_lshrrev_b32_e32 v4, 2, v0
	v_lshlrev_b32_e32 v5, 1, v0
	s_add_i32 s31, s14, s15
	s_lshr_b64 s[14:15], s[6:7], 23
	v_and_b32_e32 v4, 4, v4
	v_and_b32_e32 v5, 24, v5
	s_mul_i32 s29, s70, 0x88000
	s_mul_i32 s14, s14, s17
	v_or3_b32 v3, v3, v4, v5
	v_lshlrev_b32_e32 v4, 5, v19
	s_or_b32 s30, s29, 0x400
	s_add_i32 s31, s31, s14
	v_and_b32_e32 v20, 32, v4
	v_mul_i32_i24_e32 v4, 64, v18
	s_cmpk_gt_i32 s16, 0x5f
	v_sub_u32_e32 v1, v1, v4
	s_cselect_b32 s14, 0x10000, 0
	v_ashrrev_i16_sdwa v1, v2, sext(v1) dst_sel:DWORD dst_unused:UNUSED_PAD src0_sel:DWORD src1_sel:BYTE_0
	s_cselect_b32 s29, s30, s29
	s_add_u32 s14, s44, s14
	v_bfe_i32 v21, v1, 0, 16
	s_addc_u32 s15, s45, 0
	s_lshl_b32 s30, s70, 8
	v_and_b32_e32 v13, 15, v14
	v_add_u32_e32 v1, v20, v21
	v_mul_lo_u32 v0, v0, s27
	s_mul_i32 s17, s12, s17
	s_add_i32 s30, s28, s30
	v_mul_lo_u32 v3, v3, s6
	v_add_lshl_u32 v134, v1, v0, 1
	v_or_b32_e32 v0, s30, v13
	s_add_u32 s38, s46, s17
	v_add_lshl_u32 v132, v3, v1, 1
	v_ashrrev_i32_e32 v1, 31, v0
	s_addc_u32 s39, s47, s31
	s_add_i32 s51, s48, 0
	v_lshl_add_u64 v[0:1], v[0:1], 2, s[14:15]
	s_add_i32 m0, s51, 0x10000
	flat_load_dword v146, v[0:1]
	flat_load_dword v161, v[0:1] offset:64
	flat_load_dword v160, v[0:1] offset:128
	flat_load_dword v159, v[0:1] offset:192
	flat_load_dword v158, v[0:1] offset:512
	flat_load_dword v157, v[0:1] offset:576
	flat_load_dword v150, v[0:1] offset:640
	flat_load_dword v148, v[0:1] offset:704
	s_mul_hi_i32 s16, s70, 0x88000
	global_load_lds_dwordx4 v132, s[38:39]
	s_add_i32 m0, s51, 0x12000
	s_add_u32 s36, s8, s29
	global_load_lds_dwordx4 v128, s[38:39]
	s_addc_u32 s37, s9, s16
	s_mov_b32 m0, s51
	s_add_i32 s52, s51, 0x2000
	global_load_lds_dwordx4 v134, s[36:37]
	s_mov_b32 m0, s52
	s_add_u32 s14, s38, s10
	global_load_lds_dwordx4 v130, s[36:37]
	s_addc_u32 s15, s39, s11
	s_add_i32 m0, s51, 0x14000
	v_mov_b32_e32 v133, 0
	global_load_lds_dwordx4 v132, s[14:15]
	s_add_i32 m0, s51, 0x16000
	s_add_u32 s16, s36, 0x44000
	s_addc_u32 s17, s37, 0
	s_add_i32 s53, s51, 0x4000
	global_load_lds_dwordx4 v128, s[14:15]
	s_mov_b32 m0, s53
	s_add_i32 s54, s51, 0x6000
	global_load_lds_dwordx4 v134, s[16:17]
	s_mov_b32 m0, s54
	v_mov_b32_e32 v129, v133
	global_load_lds_dwordx4 v130, s[16:17]
	v_mov_b32_e32 v135, v133
	v_mov_b32_e32 v131, v133
	s_mov_b32 s55, 0
	v_lshl_add_u64 v[10:11], s[38:39], 0, v[132:133]
	v_lshl_add_u64 v[8:9], s[38:39], 0, v[128:129]
	v_lshl_add_u64 v[6:7], s[36:37], 0, v[134:135]
	v_lshl_add_u64 v[4:5], s[36:37], 0, v[130:131]
	v_lshl_add_u64 v[2:3], s[14:15], 0, v[132:133]
	s_cmp_lg_u32 s26, 1
	v_lshl_add_u64 v[0:1], s[14:15], 0, v[128:129]
	s_cbranch_scc1 .LBB0_1361
	s_barrier
; #define PG8_STAGE(bufoff, gbase, voff) do { _Pragma("unroll") for (int _i = 0; _i < 2; ++_i) \
;         __builtin_amdgcn_global_load_lds((const unsigned*)((const char*)(gbase) + (voff)[_i]), (LAS unsigned*)(lds + (bufoff) + ldsw + _i * 8192), 16, 0, 0); } while (0)
; #define PG8_WAIT_V(n) asm volatile("s_waitcnt vmcnt(" #n ")" ::: "memory")
; #define PG8_BAR __builtin_amdgcn_s_barrier()
; template <class Epi, class SchedT>
; DI void gemm_phase(LAS unsigned char* lds, const bf16_t* Ap, const bf16_t* Btp, const int K, const int lda, const SchedT& S, const Epi& E) {
;     ...
;     Unit cur, nxt; int ui = 0;
;     if (!S.next(0, cur)) return;
;     float pre[8]; E.prefetch(cur, wr, fr, pre);
;     f32x4 acc[2][2][4][2];
; #pragma unroll
;     for (int a = 0; a < 2; ++a)
; #pragma unroll
;         for (int b = 0; b < 2; ++b)
; #pragma unroll
;             for (int m = 0; m < 4; ++m)
; #pragma unroll
;                 for (int n = 0; n < 2; ++n) acc[a][b][m][n] = (f32x4){0.f, 0.f, 0.f, 0.f};
;     bf16x8 At[4][2], B0[2][2], B1[2][2];
;     const char* cA = (const char*)Ap + cur.aoff; const char* cB = (const char*)Btp + cur.boff;
;     PG8_STAGE(PG8_SB(0, 0), cB, voffB); PG8_STAGE(PG8_SA(0, 0), cA, voffA); PG8_STAGE(PG8_SB(0, 1), cB + hstepB, voffB); PG8_STAGE(PG8_SA(0, 1), cA + hstepA, voffA);
;     if (wr == 1) PG8_BAR;
;     PG8_WAIT_V(4); PG8_BAR;
;     PG8_STAGE(PG8_SB(1, 0), cB + kstep, voffB); PG8_STAGE(PG8_SA(1, 0), cA + kstep, voffA); PG8_STAGE(PG8_SB(1, 1), cB + hstepB + kstep, voffB);
;     PG8_WAIT_V(6); PG8_BAR;
.LBB0_1361:
	s_add_u32 s14, s8, 0xbf00000
	s_mov_b64 s[16:17], 0x80
	s_addc_u32 s15, s9, 0
	s_add_i32 m0, s51, 0x18000
	v_lshl_add_u64 v[10:11], v[10:11], 0, s[16:17]
	s_waitcnt vmcnt(4)
	s_barrier
	global_load_lds_dwordx4 v[10:11], off
	v_lshl_add_u64 v[8:9], v[8:9], 0, s[16:17]
	s_add_i32 m0, s51, 0x1a000
	s_add_i32 s56, s51, 0x8000
	global_load_lds_dwordx4 v[8:9], off
	v_lshl_add_u64 v[6:7], v[6:7], 0, s[16:17]
	s_mov_b32 m0, s56
	s_add_i32 s57, s51, 0xa000
	global_load_lds_dwordx4 v[6:7], off
	v_lshl_add_u64 v[4:5], v[4:5], 0, s[16:17]
	s_mov_b32 m0, s57
	v_lshl_add_u64 v[2:3], v[2:3], 0, s[16:17]
	global_load_lds_dwordx4 v[4:5], off
	s_add_i32 m0, s51, 0x1c000
	v_lshl_add_u64 v[0:1], v[0:1], 0, s[16:17]
	global_load_lds_dwordx4 v[2:3], off
	s_add_i32 m0, s51, 0x1e000
	s_lshr_b32 s7, s7, 26
	global_load_lds_dwordx4 v[0:1], off
	v_lshrrev_b32_e32 v0, 1, v14
	s_add_i32 s7, s6, s7
	v_or_b32_e32 v149, s28, v13
	v_and_b32_e32 v0, 24, v0
	s_ashr_i32 s58, s7, 6
	v_lshlrev_b32_e32 v1, 6, v149
	v_lshlrev_b32_e32 v2, 1, v0
	s_movk_i32 s7, 0x3c0
	v_lshlrev_b32_e32 v3, 2, v149
	v_and_or_b32 v1, v1, s7, v2
	s_lshl_b32 s7, s26, 13
	v_and_b32_e32 v3, 32, v3
	v_bitop3_b32 v3, v1, s7, v3 bitop3:0xde
	s_lshl_b32 s7, s25, 5
	s_and_b32 s7, s7, 0x60
	v_lshl_or_b32 v1, v13, 6, v2
	v_lshlrev_b32_e32 v2, 2, v13
	s_sext_i32_i16 s71, s24
	s_lshl_b32 s24, s7, 7
	v_and_b32_e32 v2, 32, v2
	v_bitop3_b32 v151, v1, s24, v2 bitop3:0xde
	v_or_b32_e32 v152, s7, v0
	v_lshrrev_b32_e32 v1, 1, v12
	v_mul_lo_u32 v0, v15, s27
	s_movk_i32 s26, 0x4400
	s_cmp_gt_i32 s6, 63
	v_mad_u64_u32 v[0:1], s[6:7], v1, s26, v[0:1]
	v_or_b32_e32 v0, v0, v16
	v_add_lshl_u32 v0, v0, v17, 1
	v_mov_b32_e32 v1, v133
	s_mov_b64 s[6:7], 0x44080
	s_waitcnt vmcnt(0)
	v_lshl_add_u64 v[136:137], v[0:1], 0, s[6:7]
	v_lshrrev_b32_e32 v1, 1, v19
	v_mul_lo_u32 v0, v18, s27
	v_mad_u64_u32 v[0:1], s[26:27], v1, s26, v[0:1]
	s_waitcnt vmcnt(6)
	v_or_b32_e32 v0, v0, v20
	s_cselect_b64 s[24:25], -1, 0
	v_add_lshl_u32 v0, v0, v21, 1
	v_mov_b32_e32 v1, v133
	s_add_i32 s64, 0, 0x10000
	s_add_i32 s65, 0, 0x14000
	s_add_i32 s59, s58, -2
	s_mov_b32 s60, 0
	s_mov_b32 s61, 1
	v_lshl_add_u64 v[138:139], v[0:1], 0, s[6:7]
	v_mov_b32_e32 v140, s95
	v_mov_b32_e32 v141, 0
	v_mov_b32_e32 v142, s92
	v_mov_b32_e32 v143, 0
	v_add_u32_e32 v153, s64, v151
	v_add_u32_e32 v154, 0, v3
	v_add_u32_e32 v155, s65, v151
	s_movk_i32 s66, 0x3800
	v_mov_b32_e32 v156, 0x358637bd
	s_mov_b32 s67, 0x800000
	s_barrier
	s_branch .LBB0_1363

;     DI bool next(int i, Unit& u) const {
;         const long L = (long)i * G + c; if (L >= nwg) return false;
;         int wgid = (int)L; { const int q = nwg / NXCD, r = nwg % NXCD, xcd = wgid % NXCD, off = wgid / NXCD; wgid = (xcd < r ? xcd * (q + 1) : r * (q + 1) + (xcd - r) * q) + off; }
;         const int nig = WGM * nN, gid = wgid / nig, fm = gid * WGM, gsz = (nM - fm) < WGM ? (nM - fm) : WGM;
;         u.pm = fm + ((wgid % nig) % gsz); u.pn = (wgid % nig) / gsz;
;         u.aoff = (size_t)u.pm * 256 * lda * 2; u.boff = (size_t)u.pn * 256 * K * 2;
;         if (MODE == 1 && u.pn >= 12) u.aoff += 1024;
;         if (MODE == 2) u.aoff += (size_t)(u.pn >> 1) * 512;
.LBB0_1363:
	s_add_i32 s55, s55, 1
	s_mul_i32 s6, s55, s60
	s_mul_hi_u32 s7, s55, s61
	s_add_i32 s7, s7, s6
	s_mul_i32 s6, s55, s61
	s_add_u32 s30, s6, s94
	s_addc_u32 s31, s7, s49
	v_cmp_gt_i64_e32 vcc, s[30:31], v[142:143]
	v_cmp_lt_i64_e64 s[6:7], s[30:31], v[140:141]
	s_cbranch_vccnz .LBB0_1365
	s_ashr_i32 s26, s30, 31
	s_lshr_b32 s26, s26, 29
	s_add_i32 s26, s30, s26
	s_ashr_i32 s27, s26, 3
	s_and_b32 s26, s26, -8
	s_sub_i32 s26, s30, s26
	s_cmp_lt_i32 s26, 0
	s_cselect_b32 s28, s50, 0xe0
	s_mul_i32 s26, s28, s26
	s_add_i32 s26, s26, s27
	s_mul_hi_i32 s27, s26, 0x92492493
	s_add_i32 s27, s27, s26
	s_lshr_b32 s28, s27, 31
	s_ashr_i32 s27, s27, 7
	s_add_i32 s27, s27, s28
	s_lshl_b32 s28, s27, 3
	s_sub_i32 s29, 64, s28
	s_min_i32 s29, s29, 8
	s_abs_i32 s30, s29
	v_cvt_f32_u32_e32 v0, s30
	s_sub_i32 s34, 0, s30
	s_mulk_i32 s27, 0xe0
	s_sub_i32 s26, s26, s27
	v_rcp_iflag_f32_e32 v0, v0
	s_abs_i32 s27, s26
	s_xor_b32 s31, s26, s29
	s_ashr_i32 s31, s31, 31
	v_mul_f32_e32 v0, 0x4f7ffffe, v0
	v_cvt_u32_f32_e32 v0, v0
	s_nop 0
	v_readfirstlane_b32 s35, v0
	s_mul_i32 s34, s34, s35
	s_mul_hi_u32 s34, s35, s34
	s_add_i32 s35, s35, s34
	s_mul_hi_u32 s34, s27, s35
	s_mul_i32 s35, s34, s30
	s_sub_i32 s27, s27, s35
	s_add_i32 s40, s34, 1
	s_sub_i32 s35, s27, s30
	s_cmp_ge_u32 s27, s30
	s_cselect_b32 s34, s40, s34
	s_cselect_b32 s27, s35, s27
	s_add_i32 s35, s34, 1
	s_cmp_ge_u32 s27, s30
	s_cselect_b32 s27, s35, s34
	s_xor_b32 s27, s27, s31
	s_sub_i32 s68, s27, s31
	s_mul_i32 s27, s68, s29
	s_sub_i32 s26, s26, s27
	s_add_i32 s69, s26, s28
	s_ashr_i32 s28, s68, 31
	s_mul_i32 s28, s12, s28
	s_mul_hi_u32 s29, s12, s68
	s_mul_i32 s26, s69, 0x88000
	s_add_i32 s28, s29, s28
	s_mul_i32 s29, s13, s68
	s_add_i32 s29, s28, s29
	s_or_b32 s30, s26, 0x400
	s_cmp_gt_i32 s68, 11
	s_mul_hi_i32 s27, s69, 0x88000
	s_mul_i32 s28, s12, s68
	s_cselect_b32 s26, s30, s26

; __global__ __launch_bounds__(512, 2) void mega(const Params p) {
	.amdhsa_kernel _Z4mega6Params
		.amdhsa_group_segment_fixed_size 0
		.amdhsa_private_segment_fixed_size 0
		.amdhsa_kernarg_size 2624
		.amdhsa_user_sgpr_count 2
		.amdhsa_user_sgpr_dispatch_ptr 0
		.amdhsa_user_sgpr_queue_ptr 0
		.amdhsa_user_sgpr_kernarg_segment_ptr 1
		.amdhsa_user_sgpr_dispatch_id 0
		.amdhsa_user_sgpr_kernarg_preload_length 0
		.amdhsa_user_sgpr_kernarg_preload_offset 0
		.amdhsa_user_sgpr_private_segment_size 0
		.amdhsa_uses_dynamic_stack 0
		.amdhsa_enable_private_segment 0
		.amdhsa_system_sgpr_workgroup_id_x 1
		.amdhsa_system_sgpr_workgroup_id_y 0
		.amdhsa_system_sgpr_workgroup_id_z 0
		.amdhsa_system_sgpr_workgroup_info 0
		.amdhsa_system_vgpr_workitem_id 2
		.amdhsa_next_free_vgpr 256
		.amdhsa_next_free_sgpr 101
		.amdhsa_accum_offset 256
		.amdhsa_reserve_vcc 1
		.amdhsa_float_round_mode_32 0
		.amdhsa_float_round_mode_16_64 0
		.amdhsa_float_denorm_mode_32 3
		.amdhsa_float_denorm_mode_16_64 3
		.amdhsa_dx10_clamp 1
		.amdhsa_ieee_mode 1
		.amdhsa_fp16_overflow 0
		.amdhsa_tg_split 0
		.amdhsa_exception_fp_ieee_invalid_op 0
		.amdhsa_exception_fp_denorm_src 0
		.amdhsa_exception_fp_ieee_div_zero 0
		.amdhsa_exception_fp_ieee_overflow 0
		.amdhsa_exception_fp_ieee_underflow 0
		.amdhsa_exception_fp_ieee_inexact 0
		.amdhsa_exception_int_div_zero 0
	.end_amdhsa_kernel

; __global__ __launch_bounds__(512, 2) void mega(const Params p) {
amdhsa.kernels:
  - .agpr_count:     0
    .args:
      - .offset:         0
        .size:           2368
        .value_kind:     by_value
      - .offset:         2368
        .size:           4
        .value_kind:     hidden_block_count_x
      - .offset:         2372
        .size:           4
        .value_kind:     hidden_block_count_y
      - .offset:         2376
        .size:           4
        .value_kind:     hidden_block_count_z
      - .offset:         2380
        .size:           2
        .value_kind:     hidden_group_size_x
      - .offset:         2382
        .size:           2
        .value_kind:     hidden_group_size_y
      - .offset:         2384
        .size:           2
        .value_kind:     hidden_group_size_z
      - .offset:         2386
        .size:           2
        .value_kind:     hidden_remainder_x
      - .offset:         2388
        .size:           2
        .value_kind:     hidden_remainder_y
      - .offset:         2390
        .size:           2
        .value_kind:     hidden_remainder_z
      - .offset:         2408
        .size:           8
        .value_kind:     hidden_global_offset_x
      - .offset:         2416
        .size:           8
        .value_kind:     hidden_global_offset_y
      - .offset:         2424
        .size:           8
        .value_kind:     hidden_global_offset_z
      - .offset:         2432
        .size:           2
        .value_kind:     hidden_grid_dims
      - .offset:         2456
        .size:           8
        .value_kind:     hidden_multigrid_sync_arg
      - .offset:         2488
        .size:           4
        .value_kind:     hidden_dynamic_lds_size
    .group_segment_fixed_size: 0
    .kernarg_segment_align: 8
    .kernarg_segment_size: 2624
    .language:       OpenCL C
    .language_version:
      - 2
      - 0
    .max_flat_workgroup_size: 512
    .name:           _Z4mega6Params
    .private_segment_fixed_size: 0
    .sgpr_count:     107
    .sgpr_spill_count: 0
    .symbol:         _Z4mega6Params.kd
    .uniform_work_group_size: 1
    .uses_dynamic_stack: false
    .vgpr_count:     256
    .vgpr_spill_count: 0
    .wavefront_size: 64
